# phase 0 weight transposes hand-written and software-pipelined two tiles deep (next tile's loads in flight during the LDS transpose, double-buffered LDS image, one barrier per tile); compiled job loop
# speedup vs baseline: 1.0011x; 1.0011x over previous
.LBB0_3:
	s_or_b64 exec, exec, s[6:7]
	s_load_dwordx16 s[68:83], s[0:1], 0x0
	s_load_dwordx16 s[52:67], s[0:1], 0x40
	s_cmpk_gt_i32 s2, 0x18bf
	v_and_b32_e32 v141, 63, v131
	v_lshrrev_b32_e32 v135, 6, v131
	v_lshlrev_b32_e32 v140, 2, v131
	v_lshrrev_b32_e32 v128, 4, v131
	v_lshrrev_b32_e32 v154, 2, v131
	v_lshlrev_b32_e32 v129, 4, v131
	v_lshlrev_b32_e32 v133, 3, v131
	s_cbranch_scc1 .LBB0_47
	s_waitcnt lgkmcnt(0)
	v_lshrrev_b32_e32 v1, 4, v131
	v_and_b32_e32 v2, 15, v131
	v_lshlrev_b32_e32 v2, 4, v2
	v_mul_u32_u24_e32 v3, 65, v1
	v_lshlrev_b32_e32 v3, 2, v3
	v_add_u32_e32 v3, v3, v2
	v_lshrrev_b32_e32 v5, 2, v131
	v_and_b32_e32 v6, 3, v131
	v_lshlrev_b32_e32 v6, 4, v6
	v_mul_u32_u24_e32 v4, 65, v6
	v_add_u32_e32 v4, v4, v5
	v_lshlrev_b32_e32 v4, 2, v4
	v_lshlrev_b32_e32 v6, 1, v6
	s_mov_b32 s8, s2
	s_cmpk_ge_i32 s8, 0x1140
	s_cbranch_scc1 .Lmy_p0_done
	s_mov_b32 s24, 0
	s_mov_b32 s30, 0x7000
	s_mov_b32 s31, 4
	s_mov_b32 s32, 11
	s_mov_b32 s33, 0x1a00000
	s_mov_b32 s34, s80
	s_mov_b32 s35, s81
	s_cmpk_ge_i32 s8, 0x700
	s_cselect_b32 s24, 0x700, s24
	s_cselect_b32 s30, 0x1000, s30
	s_cselect_b32 s31, 5, s31
	s_cselect_b32 s32, 12, s32
	s_cselect_b32 s33, 0x2800000, s33
	s_cselect_b32 s34, s60, s34
	s_cselect_b32 s35, s61, s35
	s_cmpk_ge_i32 s8, 0x900
	s_cselect_b32 s24, 0x900, s24
	s_cselect_b32 s30, 0x6000, s30
	s_cselect_b32 s31, 4, s31
	s_cselect_b32 s32, 11, s32
	s_cselect_b32 s33, 0x0, s33
	s_cselect_b32 s34, s36, s34
	s_cselect_b32 s35, s37, s35
	s_cmpk_ge_i32 s8, 0xf00
	s_cselect_b32 s24, 0xf00, s24
	s_cselect_b32 s30, 0x1000, s30
	s_cselect_b32 s31, 5, s31
	s_cselect_b32 s32, 12, s32
	s_cselect_b32 s33, 0xc00000, s33
	s_cselect_b32 s34, s46, s34
	s_cselect_b32 s35, s47, s35
	s_cmpk_ge_i32 s8, 0x1100
	s_cselect_b32 s24, 0x1100, s24
	s_cselect_b32 s30, 0x400, s30
	s_cselect_b32 s31, 2, s31
	s_cselect_b32 s32, 9, s32
	s_cselect_b32 s33, 0x1000000, s33
	s_cselect_b32 s34, s38, s34
	s_cselect_b32 s35, s39, s35
	s_sub_i32 s28, s8, s24
	s_lshr_b32 s29, s28, 4
	s_and_b32 s25, s28, 15
	s_cmpk_ge_i32 s8, 0x1100
	s_cselect_b32 s29, s29, 0
	s_cselect_b32 s28, s25, s28
	s_lshl_b32 s25, 1, s31
	s_sub_i32 s25, s25, 1
	s_and_b32 s26, s28, s25
	s_lshr_b32 s27, s28, s31
	s_lshl_b32 s25, s26, 6
	s_mul_i32 s25, s25, s30
	s_lshl_b32 s24, s27, 8
	s_add_i32 s25, s25, s24
	s_lshl_b32 s24, s29, 18
	s_add_i32 s25, s25, s24
	s_add_u32 s12, s34, s25
	s_addc_u32 s13, s35, 0
	s_lshl_b32 s14, s30, 4
	s_add_i32 s24, s32, 6
	s_lshl_b32 s25, s27, s24
	s_lshl_b32 s24, s26, 7
	s_add_i32 s25, s25, s24
	s_lshl_b32 s24, s29, 17
	s_add_i32 s25, s25, s24
	s_add_i32 s25, s25, s33
	s_add_u32 s16, s50, s25
	s_addc_u32 s17, s51, 0
	s_mov_b32 s18, s32
	v_mul_lo_u32 v8, v1, s30
	v_add_u32_e32 v8, v8, v2
	global_load_dwordx4 v[16:19], v8, s[12:13] nt
	s_add_u32 s12, s12, s14
	s_addc_u32 s13, s13, 0
	global_load_dwordx4 v[20:23], v8, s[12:13] nt
	s_add_u32 s12, s12, s14
	s_addc_u32 s13, s13, 0
	global_load_dwordx4 v[24:27], v8, s[12:13] nt
	s_add_u32 s12, s12, s14
	s_addc_u32 s13, s13, 0
	global_load_dwordx4 v[28:31], v8, s[12:13] nt
.Lmy_p0_loop:
	s_add_i32 s9, s8, s3
	s_mov_b32 s10, 0
	s_cmpk_ge_i32 s9, 0x1140
	s_cbranch_scc1 .Lmy_p0_np0
	s_mov_b32 s10, 1
	s_mov_b32 s24, 0
	s_mov_b32 s30, 0x7000
	s_mov_b32 s31, 4
	s_mov_b32 s32, 11
	s_mov_b32 s33, 0x1a00000
	s_mov_b32 s34, s80
	s_mov_b32 s35, s81
	s_cmpk_ge_i32 s9, 0x700
	s_cselect_b32 s24, 0x700, s24
	s_cselect_b32 s30, 0x1000, s30
	s_cselect_b32 s31, 5, s31
	s_cselect_b32 s32, 12, s32
	s_cselect_b32 s33, 0x2800000, s33
	s_cselect_b32 s34, s60, s34
	s_cselect_b32 s35, s61, s35
	s_cmpk_ge_i32 s9, 0x900
	s_cselect_b32 s24, 0x900, s24
	s_cselect_b32 s30, 0x6000, s30
	s_cselect_b32 s31, 4, s31
	s_cselect_b32 s32, 11, s32
	s_cselect_b32 s33, 0x0, s33
	s_cselect_b32 s34, s36, s34
	s_cselect_b32 s35, s37, s35
	s_cmpk_ge_i32 s9, 0xf00
	s_cselect_b32 s24, 0xf00, s24
	s_cselect_b32 s30, 0x1000, s30
	s_cselect_b32 s31, 5, s31
	s_cselect_b32 s32, 12, s32
	s_cselect_b32 s33, 0xc00000, s33
	s_cselect_b32 s34, s46, s34
	s_cselect_b32 s35, s47, s35
	s_cmpk_ge_i32 s9, 0x1100
	s_cselect_b32 s24, 0x1100, s24
	s_cselect_b32 s30, 0x400, s30
	s_cselect_b32 s31, 2, s31
	s_cselect_b32 s32, 9, s32
	s_cselect_b32 s33, 0x1000000, s33
	s_cselect_b32 s34, s38, s34
	s_cselect_b32 s35, s39, s35
	s_sub_i32 s28, s9, s24
	s_lshr_b32 s29, s28, 4
	s_and_b32 s25, s28, 15
	s_cmpk_ge_i32 s9, 0x1100
	s_cselect_b32 s29, s29, 0
	s_cselect_b32 s28, s25, s28
	s_lshl_b32 s25, 1, s31
	s_sub_i32 s25, s25, 1
	s_and_b32 s26, s28, s25
	s_lshr_b32 s27, s28, s31
	s_lshl_b32 s25, s26, 6
	s_mul_i32 s25, s25, s30
	s_lshl_b32 s24, s27, 8
	s_add_i32 s25, s25, s24
	s_lshl_b32 s24, s29, 18
	s_add_i32 s25, s25, s24
	s_add_u32 s12, s34, s25
	s_addc_u32 s13, s35, 0
	s_lshl_b32 s14, s30, 4
	s_add_i32 s24, s32, 6
	s_lshl_b32 s25, s27, s24
	s_lshl_b32 s24, s26, 7
	s_add_i32 s25, s25, s24
	s_lshl_b32 s24, s29, 17
	s_add_i32 s25, s25, s24
	s_add_i32 s25, s25, s33
	s_add_u32 s20, s50, s25
	s_addc_u32 s21, s51, 0
	s_mov_b32 s22, s32
	v_mul_lo_u32 v9, v1, s30
	v_add_u32_e32 v9, v9, v2
	global_load_dwordx4 v[32:35], v9, s[12:13] nt
	s_add_u32 s12, s12, s14
	s_addc_u32 s13, s13, 0
	global_load_dwordx4 v[36:39], v9, s[12:13] nt
	s_add_u32 s12, s12, s14
	s_addc_u32 s13, s13, 0
	global_load_dwordx4 v[40:43], v9, s[12:13] nt
	s_add_u32 s12, s12, s14
	s_addc_u32 s13, s13, 0
	global_load_dwordx4 v[44:47], v9, s[12:13] nt
.Lmy_p0_np0:
	s_cmp_lg_u32 s10, 0
	s_cbranch_scc1 .Lmy_p0_w40
	s_waitcnt vmcnt(0)
	s_branch .Lmy_p0_wc0
.Lmy_p0_w40:
	s_waitcnt vmcnt(4)
.Lmy_p0_wc0:
	ds_write_b32 v3, v16 offset:0
	ds_write_b32 v3, v17 offset:4
	ds_write_b32 v3, v18 offset:8
	ds_write_b32 v3, v19 offset:12
	ds_write_b32 v3, v20 offset:4160
	ds_write_b32 v3, v21 offset:4164
	ds_write_b32 v3, v22 offset:4168
	ds_write_b32 v3, v23 offset:4172
	ds_write_b32 v3, v24 offset:8320
	ds_write_b32 v3, v25 offset:8324
	ds_write_b32 v3, v26 offset:8328
	ds_write_b32 v3, v27 offset:8332
	ds_write_b32 v3, v28 offset:12480
	ds_write_b32 v3, v29 offset:12484
	ds_write_b32 v3, v30 offset:12488
	ds_write_b32 v3, v31 offset:12492
	s_waitcnt lgkmcnt(0)
	s_barrier
	ds_read_b32 v48, v4 offset:0
	ds_read_b32 v49, v4 offset:260
	ds_read_b32 v50, v4 offset:520
	ds_read_b32 v51, v4 offset:780
	ds_read_b32 v52, v4 offset:1040
	ds_read_b32 v53, v4 offset:1300
	ds_read_b32 v54, v4 offset:1560
	ds_read_b32 v55, v4 offset:1820
	ds_read_b32 v56, v4 offset:2080
	ds_read_b32 v57, v4 offset:2340
	ds_read_b32 v58, v4 offset:2600
	ds_read_b32 v59, v4 offset:2860
	ds_read_b32 v60, v4 offset:3120
	ds_read_b32 v61, v4 offset:3380
	ds_read_b32 v62, v4 offset:3640
	ds_read_b32 v63, v4 offset:3900
	v_lshlrev_b32_e64 v7, s18, v5
	v_add_u32_e32 v7, v7, v6
	s_waitcnt lgkmcnt(0)
	v_cvt_pk_bf16_f32 v48, v48, v49
	v_cvt_pk_bf16_f32 v49, v50, v51
	v_cvt_pk_bf16_f32 v50, v52, v53
	v_cvt_pk_bf16_f32 v51, v54, v55
	v_cvt_pk_bf16_f32 v52, v56, v57
	v_cvt_pk_bf16_f32 v53, v58, v59
	v_cvt_pk_bf16_f32 v54, v60, v61
	v_cvt_pk_bf16_f32 v55, v62, v63
	global_store_dwordx4 v7, v[48:51], s[16:17]
	global_store_dwordx4 v7, v[52:55], s[16:17] offset:16
	s_mov_b32 s8, s9
	s_mov_b32 s16, s20
	s_mov_b32 s17, s21
	s_mov_b32 s18, s22
	s_cmp_eq_u32 s10, 0
	s_cbranch_scc1 .Lmy_p0_done
	s_add_i32 s9, s8, s3
	s_mov_b32 s10, 0
	s_cmpk_ge_i32 s9, 0x1140
	s_cbranch_scc1 .Lmy_p0_np1
	s_mov_b32 s10, 1
	s_mov_b32 s24, 0
	s_mov_b32 s30, 0x7000
	s_mov_b32 s31, 4
	s_mov_b32 s32, 11
	s_mov_b32 s33, 0x1a00000
	s_mov_b32 s34, s80
	s_mov_b32 s35, s81
	s_cmpk_ge_i32 s9, 0x700
	s_cselect_b32 s24, 0x700, s24
	s_cselect_b32 s30, 0x1000, s30
	s_cselect_b32 s31, 5, s31
	s_cselect_b32 s32, 12, s32
	s_cselect_b32 s33, 0x2800000, s33
	s_cselect_b32 s34, s60, s34
	s_cselect_b32 s35, s61, s35
	s_cmpk_ge_i32 s9, 0x900
	s_cselect_b32 s24, 0x900, s24
	s_cselect_b32 s30, 0x6000, s30
	s_cselect_b32 s31, 4, s31
	s_cselect_b32 s32, 11, s32
	s_cselect_b32 s33, 0x0, s33
	s_cselect_b32 s34, s36, s34
	s_cselect_b32 s35, s37, s35
	s_cmpk_ge_i32 s9, 0xf00
	s_cselect_b32 s24, 0xf00, s24
	s_cselect_b32 s30, 0x1000, s30
	s_cselect_b32 s31, 5, s31
	s_cselect_b32 s32, 12, s32
	s_cselect_b32 s33, 0xc00000, s33
	s_cselect_b32 s34, s46, s34
	s_cselect_b32 s35, s47, s35
	s_cmpk_ge_i32 s9, 0x1100
	s_cselect_b32 s24, 0x1100, s24
	s_cselect_b32 s30, 0x400, s30
	s_cselect_b32 s31, 2, s31
	s_cselect_b32 s32, 9, s32
	s_cselect_b32 s33, 0x1000000, s33
	s_cselect_b32 s34, s38, s34
	s_cselect_b32 s35, s39, s35
	s_sub_i32 s28, s9, s24
	s_lshr_b32 s29, s28, 4
	s_and_b32 s25, s28, 15
	s_cmpk_ge_i32 s9, 0x1100
	s_cselect_b32 s29, s29, 0
	s_cselect_b32 s28, s25, s28
	s_lshl_b32 s25, 1, s31
	s_sub_i32 s25, s25, 1
	s_and_b32 s26, s28, s25
	s_lshr_b32 s27, s28, s31
	s_lshl_b32 s25, s26, 6
	s_mul_i32 s25, s25, s30
	s_lshl_b32 s24, s27, 8
	s_add_i32 s25, s25, s24
	s_lshl_b32 s24, s29, 18
	s_add_i32 s25, s25, s24
	s_add_u32 s12, s34, s25
	s_addc_u32 s13, s35, 0
	s_lshl_b32 s14, s30, 4
	s_add_i32 s24, s32, 6
	s_lshl_b32 s25, s27, s24
	s_lshl_b32 s24, s26, 7
	s_add_i32 s25, s25, s24
	s_lshl_b32 s24, s29, 17
	s_add_i32 s25, s25, s24
	s_add_i32 s25, s25, s33
	s_add_u32 s20, s50, s25
	s_addc_u32 s21, s51, 0
	s_mov_b32 s22, s32
	v_mul_lo_u32 v8, v1, s30
	v_add_u32_e32 v8, v8, v2
	global_load_dwordx4 v[16:19], v8, s[12:13] nt
	s_add_u32 s12, s12, s14
	s_addc_u32 s13, s13, 0
	global_load_dwordx4 v[20:23], v8, s[12:13] nt
	s_add_u32 s12, s12, s14
	s_addc_u32 s13, s13, 0
	global_load_dwordx4 v[24:27], v8, s[12:13] nt
	s_add_u32 s12, s12, s14
	s_addc_u32 s13, s13, 0
	global_load_dwordx4 v[28:31], v8, s[12:13] nt

.Lmy_p0_wc1:
	ds_write_b32 v3, v32 offset:16640
	ds_write_b32 v3, v33 offset:16644
	ds_write_b32 v3, v34 offset:16648
	ds_write_b32 v3, v35 offset:16652
	ds_write_b32 v3, v36 offset:20800
	ds_write_b32 v3, v37 offset:20804
	ds_write_b32 v3, v38 offset:20808
	ds_write_b32 v3, v39 offset:20812
	ds_write_b32 v3, v40 offset:24960
	ds_write_b32 v3, v41 offset:24964
	ds_write_b32 v3, v42 offset:24968
	ds_write_b32 v3, v43 offset:24972
	ds_write_b32 v3, v44 offset:29120
	ds_write_b32 v3, v45 offset:29124
	ds_write_b32 v3, v46 offset:29128
	ds_write_b32 v3, v47 offset:29132
	s_waitcnt lgkmcnt(0)
	s_barrier
	ds_read_b32 v48, v4 offset:16640
	ds_read_b32 v49, v4 offset:16900
	ds_read_b32 v50, v4 offset:17160
	ds_read_b32 v51, v4 offset:17420
	ds_read_b32 v52, v4 offset:17680
	ds_read_b32 v53, v4 offset:17940
	ds_read_b32 v54, v4 offset:18200
	ds_read_b32 v55, v4 offset:18460
	ds_read_b32 v56, v4 offset:18720
	ds_read_b32 v57, v4 offset:18980
	ds_read_b32 v58, v4 offset:19240
	ds_read_b32 v59, v4 offset:19500
	ds_read_b32 v60, v4 offset:19760
	ds_read_b32 v61, v4 offset:20020
	ds_read_b32 v62, v4 offset:20280
	ds_read_b32 v63, v4 offset:20540
	v_lshlrev_b32_e64 v7, s18, v5
	v_add_u32_e32 v7, v7, v6
	s_waitcnt lgkmcnt(0)
	v_cvt_pk_bf16_f32 v48, v48, v49
	v_cvt_pk_bf16_f32 v49, v50, v51
	v_cvt_pk_bf16_f32 v50, v52, v53
	v_cvt_pk_bf16_f32 v51, v54, v55
	v_cvt_pk_bf16_f32 v52, v56, v57
	v_cvt_pk_bf16_f32 v53, v58, v59
	v_cvt_pk_bf16_f32 v54, v60, v61
	v_cvt_pk_bf16_f32 v55, v62, v63
	global_store_dwordx4 v7, v[48:51], s[16:17]
	global_store_dwordx4 v7, v[52:55], s[16:17] offset:16
	s_mov_b32 s8, s9
	s_mov_b32 s16, s20
	s_mov_b32 s17, s21
	s_mov_b32 s18, s22
	s_cmp_eq_u32 s10, 0
	s_cbranch_scc1 .Lmy_p0_done
	s_branch .Lmy_p0_loop
.Lmy_p0_done:
	s_waitcnt vmcnt(0)
	s_barrier
	s_mov_b32 s0, 0x979a371
	v_cvt_f64_u32_e32 v[2:3], v141
	s_mov_b32 s1, 0xbfca934f
	v_mul_f64 v[2:3], v[2:3], s[0:1]
	v_rndne_f64_e32 v[4:5], v[2:3]
	s_mov_b32 s0, 0x3b39803f
	v_add_f64 v[6:7], v[2:3], -v[4:5]
	s_mov_b32 s1, 0x3c7abc9e
	v_mul_f64 v[8:9], v[6:7], s[0:1]
	s_mov_b32 s0, 0xfefa39ef
	s_mov_b32 s1, 0x3fe62e42
	v_fmac_f64_e32 v[8:9], s[0:1], v[6:7]
	s_mov_b32 s0, 0x6a5dcb37
	v_mov_b32_e32 v6, 0xfca7ab0c
	v_mov_b32_e32 v7, 0x3e928af3
	s_mov_b32 s1, 0x3e5ade15
	v_fmac_f64_e32 v[6:7], s[0:1], v[8:9]
	v_mov_b32_e32 v10, 0x623fde64
	v_mov_b32_e32 v11, 0x3ec71dee
	v_fmac_f64_e32 v[10:11], v[8:9], v[6:7]
	v_mov_b32_e32 v6, 0x7c89e6b0
	v_mov_b32_e32 v7, 0x3efa0199
	v_fmac_f64_e32 v[6:7], v[8:9], v[10:11]
	v_mov_b32_e32 v10, 0x14761f6e
	v_mov_b32_e32 v11, 0x3f2a01a0
	v_fmac_f64_e32 v[10:11], v[8:9], v[6:7]
	v_mov_b32_e32 v6, 0x1852b7b0
	v_mov_b32_e32 v7, 0x3f56c16c
	v_fmac_f64_e32 v[6:7], v[8:9], v[10:11]
	v_mov_b32_e32 v10, 0x11122322
	v_mov_b32_e32 v11, 0x3f811111
	v_fmac_f64_e32 v[10:11], v[8:9], v[6:7]
	v_mov_b32_e32 v6, 0x555502a1
	v_mov_b32_e32 v7, 0x3fa55555
	v_fmac_f64_e32 v[6:7], v[8:9], v[10:11]
	v_mov_b32_e32 v10, 0x55555511
	v_mov_b32_e32 v11, 0x3fc55555
	s_add_u32 s6, s50, 0x1080000
	v_fmac_f64_e32 v[10:11], v[8:9], v[6:7]
	v_mov_b32_e32 v6, 11
	v_mov_b32_e32 v7, 0x3fe00000
	s_mov_b32 s0, 0
	s_addc_u32 s7, s51, 0
	v_fmac_f64_e32 v[6:7], v[8:9], v[10:11]
	s_mov_b32 s1, 0x40900000
	s_add_u32 s8, s50, 0x1200000
	v_fma_f64 v[6:7], v[8:9], v[6:7], 1.0
	v_cmp_nlt_f64_e32 vcc, s[0:1], v[2:3]
	s_mov_b32 s0, 0
	s_addc_u32 s9, s51, 0
	v_fma_f64 v[6:7], v[8:9], v[6:7], 1.0
	v_cvt_i32_f64_e32 v4, v[4:5]
	s_mov_b32 s1, 0xc090cc00
	s_add_u32 s10, s50, 0x1600000
	v_ldexp_f64 v[4:5], v[6:7], v4
	v_mov_b32_e32 v6, 0x7ff00000
	v_cmp_ngt_f64_e64 s[0:1], s[0:1], v[2:3]
	s_addc_u32 s11, s51, 0
	v_cndmask_b32_e32 v5, v6, v5, vcc
	s_and_b64 vcc, s[0:1], vcc
	s_add_u32 s12, s50, 0x10c0000
	s_addc_u32 s13, s51, 0
	s_add_u32 s30, s50, 0x1000000
	s_addc_u32 s31, s51, 0
	v_cndmask_b32_e64 v3, 0, v5, s[0:1]
	v_cndmask_b32_e32 v2, 0, v4, vcc
	s_add_u32 s14, s50, 0xc00000
	v_cvt_f32_f64_e32 v27, v[2:3]
	v_lshlrev_b32_e32 v29, 7, v135
	v_mul_u32_u24_e32 v2, 0x380, v135
	v_lshlrev_b32_e32 v3, 2, v141
	s_addc_u32 s15, s51, 0
	v_add3_u32 v30, v29, v2, v3
	v_lshlrev_b32_e32 v31, 2, v131
	v_and_b32_e32 v2, 0x3c0, v131
	s_add_u32 s16, s50, 0x2800000
	v_lshl_or_b32 v32, v2, 2, v3
	v_and_b32_e32 v2, 60, v31
	v_mov_b32_e32 v11, 0
	v_and_b32_e32 v14, 48, v129
	s_addc_u32 s17, s51, 0
	s_movk_i32 s0, 0x200
	v_lshlrev_b32_e32 v12, 2, v2
	v_and_b32_e32 v3, 0x3fc, v131
	v_mul_u32_u24_e32 v4, 0x41, v14
	s_add_u32 s18, s50, 0x1a00000
	v_mov_b32_e32 v13, v11
	s_mov_b32 s20, 0x6dc9c883
	v_or_b32_e32 v1, 0xff9f0000, v131
	v_and_b32_e32 v15, 0x7f, v131
	v_or_b32_e32 v26, 0xffaf0000, v131
	v_cmp_gt_u32_e64 s[0:1], s0, v131
	v_lshlrev_b32_e32 v28, 5, v135
	v_mul_u32_u24_e32 v33, 0x104, v128
	v_add_u32_e32 v34, 16, v128
	v_add_u32_e32 v35, 32, v128
	v_add_u32_e32 v36, 48, v128
	v_lshl_add_u32 v37, v4, 2, v3
	s_addc_u32 s19, s51, 0
	v_lshl_add_u64 v[16:17], s[46:47], 0, v[12:13]
	v_lshl_add_u64 v[18:19], s[36:37], 0, v[12:13]
	s_waitcnt lgkmcnt(0)
	v_lshl_add_u64 v[20:21], s[60:61], 0, v[12:13]
	v_lshl_add_u64 v[22:23], s[80:81], 0, v[12:13]
	v_add_u32_e32 v13, 0xffffff00, v131
	s_movk_i32 s33, 0x7fff
	s_mov_b32 s21, 0x3fc45f30
	s_movk_i32 s34, 0x3000
	s_mov_b32 s35, 0x3c000
	s_mov_b32 s36, 0x3f000
	s_mov_b32 s37, 0x42000
	s_mov_b32 s46, 0x45000
	s_mov_b32 s47, 0x48000
	v_lshlrev_b32_e32 v24, 2, v2
	s_mov_b32 s60, 0x4b000
	s_mov_b32 s61, 0x4e000
	s_mov_b32 s80, 0x51000
	s_mov_b32 s81, 0x54000
	s_mov_b32 s84, 0x57000
	s_mov_b32 s85, 0x5a000
	s_mov_b32 s86, 0x5d000
	s_mov_b32 s87, 0x7060302
	s_movk_i32 s88, 0x7000
	s_mov_b32 s89, s2
	s_mov_b32 s23, 0
	s_branch .LBB0_6

.Lmy_p0_skip:
	s_cmpk_lt_i32 s89, 0x300
	s_cbranch_scc1 .Lmy_p0_ok
	s_cmpk_ge_i32 s89, 0x1440
	s_cbranch_scc1 .Lmy_p0_ok
	s_add_i32 s89, s89, s3
	s_branch .Lmy_p0_skip
.Lmy_p0_ok:
	s_cmpk_lt_i32 s89, 0x18c0
	s_cbranch_scc0 .LBB0_47
